# v18: compact VOP2 (e32) encodings for the 16 row-sum adds in the attention fast loops; otherwise v17
# speedup vs baseline: 1.0024x; 1.0024x over previous
; #define MFMA32(a, b, c) __builtin_amdgcn_mfma_f32_32x32x16_bf16((a), (b), (c), 0, 0, 0)
; __device__ __forceinline__ bf16x8 cat8(s16x4 lo, s16x4 hi) { return (bf16x8){lo[0], lo[1], lo[2], lo[3], hi[0], hi[1], hi[2], hi[3]}; }
; template <int KS>
; __device__ __forceinline__ void flash_fast_tile2(ldsp Ks, ldsp Vs, const FragMap<KS>& M, const bf16x8 (&qf)[KS], f32x16 (&o)[4], float& mc, float& l) {
;     ...
;         float ps0 = 0.f, ps1 = 0.f;
; #pragma unroll
;         for (int r = 0; r < 16; r += 2) { s0[r] = __builtin_amdgcn_exp2f(s0[r] - mc); s0[r + 1] = __builtin_amdgcn_exp2f(s0[r + 1] - mc); ps0 += s0[r]; ps1 += s0[r + 1]; }
;         l += ps0 + ps1;
;         const bf16x8 p0 = pack8<0>(s0), p1 = pack8<1>(s0);
; #pragma unroll
;         for (int b = 0; b < 4; ++b) {
;             o[b] = MFMA32(cat8(vl[2 * b], vh[2 * b]), p0, o[b]);
;             o[b] = MFMA32(cat8(vl[2 * b + 1], vh[2 * b + 1]), p1, o[b]); }
.LBB0_436:
	v_exp_f32_e32 v66, v66
	v_exp_f32_e32 v67, v67
	v_exp_f32_e32 v68, v68
	v_exp_f32_e32 v69, v69
	v_exp_f32_e32 v70, v70
	v_exp_f32_e32 v71, v71
	v_exp_f32_e32 v72, v72
	v_exp_f32_e32 v73, v73
	v_add_f32_e32 v212, v66, v68
	v_add_f32_e32 v213, v67, v69
	v_cvt_pk_bf16_f32 v66, v66, v67
	v_cvt_pk_bf16_f32 v67, v68, v69
	v_cvt_pk_bf16_f32 v68, v70, v71
	v_cvt_pk_bf16_f32 v69, v72, v73
	v_exp_f32_e32 v74, v74
	v_exp_f32_e32 v75, v75
	v_mfma_f32_32x32x16_bf16 v[50:65], v[142:145], v[66:69], v[50:65]
	s_waitcnt lgkmcnt(10)
	v_mfma_f32_32x32x16_bf16 v[34:49], v[134:137], v[66:69], v[34:49]
	v_exp_f32_e32 v76, v76
	v_exp_f32_e32 v77, v77
	v_exp_f32_e32 v78, v78
	v_exp_f32_e32 v79, v79
	v_exp_f32_e32 v80, v80
	v_exp_f32_e32 v81, v81
	s_waitcnt lgkmcnt(6)
	v_mfma_f32_32x32x16_bf16 v[18:33], v[126:129], v[66:69], v[18:33]
	v_add_f32_e32 v212, v70, v212
	v_add_f32_e32 v213, v71, v213
	v_cvt_pk_bf16_f32 v70, v74, v75
	v_add_f32_e32 v212, v72, v212
	v_add_f32_e32 v213, v73, v213
	v_cvt_pk_bf16_f32 v71, v76, v77
	v_cvt_pk_bf16_f32 v72, v78, v79
	v_cvt_pk_bf16_f32 v73, v80, v81
	v_add_f32_e32 v212, v74, v212
	v_add_f32_e32 v213, v75, v213
	s_waitcnt lgkmcnt(2)
	v_mfma_f32_32x32x16_bf16 v[2:17], v[114:117], v[66:69], v[2:17]
	v_add_f32_e32 v212, v76, v212
	v_add_f32_e32 v213, v77, v213
	s_movk_i32 s10, 0x2000
	v_add_f32_e32 v212, v78, v212
	v_add_f32_e32 v213, v79, v213
	s_mov_b64 s[0:1], 0
	v_add_f32_e32 v212, v80, v212
	v_add_f32_e32 v213, v81, v213
	s_andn2_b64 vcc, exec, s[4:5]
	v_add_f32_e32 v211, v212, v213
	v_mfma_f32_32x32x16_bf16 v[50:65], v[138:141], v[70:73], v[50:65]
	v_add_f32_e32 v195, v195, v211
	v_mfma_f32_32x32x16_bf16 v[34:49], v[130:133], v[70:73], v[34:49]
	v_mfma_f32_32x32x16_bf16 v[18:33], v[122:125], v[70:73], v[18:33]
	s_waitcnt lgkmcnt(0)
	v_mfma_f32_32x32x16_bf16 v[2:17], v[118:121], v[70:73], v[2:17]
	s_cbranch_vccz .LBB0_434

; #define MFMA32(a, b, c) __builtin_amdgcn_mfma_f32_32x32x16_bf16((a), (b), (c), 0, 0, 0)
; __device__ __forceinline__ bf16x8 cat8(s16x4 lo, s16x4 hi) { return (bf16x8){lo[0], lo[1], lo[2], lo[3], hi[0], hi[1], hi[2], hi[3]}; }
; template <int KS>
; __device__ __forceinline__ void flash_fast_tile2(ldsp Ks, ldsp Vs, const FragMap<KS>& M, const bf16x8 (&qf)[KS], f32x16 (&o)[4], float& mc, float& l) {
;     ...
;         float ps0 = 0.f, ps1 = 0.f;
; #pragma unroll
;         for (int r = 0; r < 16; r += 2) { s0[r] = __builtin_amdgcn_exp2f(s0[r] - mc); s0[r + 1] = __builtin_amdgcn_exp2f(s0[r + 1] - mc); ps0 += s0[r]; ps1 += s0[r + 1]; }
;         l += ps0 + ps1;
;         const bf16x8 p0 = pack8<0>(s0), p1 = pack8<1>(s0);
; #pragma unroll
;         for (int b = 0; b < 4; ++b) {
;             o[b] = MFMA32(cat8(vl[2 * b], vh[2 * b]), p0, o[b]);
;             o[b] = MFMA32(cat8(vl[2 * b + 1], vh[2 * b + 1]), p1, o[b]); }
.LBB0_460:
	v_exp_f32_e32 v80, v80
	v_exp_f32_e32 v81, v81
	v_exp_f32_e32 v82, v82
	v_exp_f32_e32 v83, v83
	v_exp_f32_e32 v84, v84
	v_exp_f32_e32 v85, v85
	v_exp_f32_e32 v86, v86
	v_exp_f32_e32 v87, v87
	v_add_f32_e32 v252, v80, v82
	v_add_f32_e32 v253, v81, v83
	v_cvt_pk_bf16_f32 v80, v80, v81
	v_cvt_pk_bf16_f32 v81, v82, v83
	v_cvt_pk_bf16_f32 v82, v84, v85
	v_cvt_pk_bf16_f32 v83, v86, v87
	v_exp_f32_e32 v88, v88
	v_exp_f32_e32 v89, v89
	v_mfma_f32_32x32x16_bf16 v[64:79], v[144:147], v[80:83], v[64:79]
	s_waitcnt lgkmcnt(10)
	v_mfma_f32_32x32x16_bf16 v[48:63], v[136:139], v[80:83], v[48:63]
	v_exp_f32_e32 v90, v90
	v_exp_f32_e32 v91, v91
	v_exp_f32_e32 v92, v92
	v_exp_f32_e32 v93, v93
	v_exp_f32_e32 v94, v94
	v_exp_f32_e32 v95, v95
	s_waitcnt lgkmcnt(6)
	v_mfma_f32_32x32x16_bf16 v[32:47], v[128:131], v[80:83], v[32:47]
	v_add_f32_e32 v252, v84, v252
	v_add_f32_e32 v253, v85, v253
	v_cvt_pk_bf16_f32 v84, v88, v89
	v_add_f32_e32 v252, v86, v252
	v_add_f32_e32 v253, v87, v253
	v_cvt_pk_bf16_f32 v85, v90, v91
	v_cvt_pk_bf16_f32 v86, v92, v93
	v_cvt_pk_bf16_f32 v87, v94, v95
	v_add_f32_e32 v252, v88, v252
	v_add_f32_e32 v253, v89, v253
	s_waitcnt lgkmcnt(2)
	v_mfma_f32_32x32x16_bf16 v[16:31], v[116:119], v[80:83], v[16:31]
	v_add_f32_e32 v252, v90, v252
	v_add_f32_e32 v253, v91, v253
	s_movk_i32 s28, 0x2000
	v_add_f32_e32 v252, v92, v252
	v_add_f32_e32 v253, v93, v253
	s_mov_b64 s[0:1], 0
	v_add_f32_e32 v252, v94, v252
	v_add_f32_e32 v253, v95, v253
	s_andn2_b64 vcc, exec, s[4:5]
	v_add_f32_e32 v211, v252, v253
	v_mfma_f32_32x32x16_bf16 v[64:79], v[140:143], v[84:87], v[64:79]
	v_add_f32_e32 v195, v195, v211
	v_mfma_f32_32x32x16_bf16 v[48:63], v[132:135], v[84:87], v[48:63]
	v_mfma_f32_32x32x16_bf16 v[32:47], v[124:127], v[84:87], v[32:47]
	s_waitcnt lgkmcnt(0)
	v_mfma_f32_32x32x16_bf16 v[16:31], v[120:123], v[84:87], v[16:31]
	s_cbranch_vccz .LBB0_458
